# safe stack + HGRN2 output pass without its redundant top-of-unit workgroup barrier
# speedup vs baseline: 1.0073x; 1.0073x over previous
.LBB0_117:
	v_and_b32_e32 v10, 0xffff, v24
	v_lshrrev_b32_e32 v11, 16, v24
	s_mov_b32 s0, 0xffff0000
	v_lshl_or_b32 v10, v28, 16, v10
	v_and_or_b32 v11, v28, s0, v11
	v_lshlrev_b32_e32 v72, 16, v79
	v_and_b32_e32 v73, 0xffff0000, v79
	ds_write2_b32 v122, v10, v11 offset1:36
	v_and_b32_e32 v10, 0xffff, v25
	v_lshrrev_b32_e32 v11, 16, v25
	v_lshlrev_b32_e32 v66, 16, v89
	v_and_b32_e32 v67, 0xffff0000, v89
	v_pk_add_f32 v[70:71], v[72:73], 0 op_sel_hi:[1,0]
	v_lshl_or_b32 v10, v29, 16, v10
	v_and_or_b32 v11, v29, s0, v11
	v_lshlrev_b32_e32 v62, 16, v110
	v_and_b32_e32 v63, 0xffff0000, v110
	v_pk_add_f32 v[68:69], v[70:71], v[66:67]
	ds_write2_b32 v122, v10, v11 offset0:72 offset1:108
	v_and_b32_e32 v10, 0xffff, v26
	v_lshrrev_b32_e32 v11, 16, v26
	v_lshlrev_b32_e32 v58, 16, v111
	v_and_b32_e32 v59, 0xffff0000, v111
	v_pk_add_f32 v[64:65], v[68:69], v[62:63]
	v_lshl_or_b32 v10, v30, 16, v10
	v_and_or_b32 v11, v30, s0, v11
	v_lshlrev_b32_e32 v54, 16, v112
	v_and_b32_e32 v55, 0xffff0000, v112
	v_pk_add_f32 v[60:61], v[64:65], v[58:59]
	ds_write2_b32 v122, v10, v11 offset0:144 offset1:180
	v_and_b32_e32 v10, 0xffff, v27
	v_lshrrev_b32_e32 v11, 16, v27
	v_lshlrev_b32_e32 v50, 16, v113
	v_and_b32_e32 v51, 0xffff0000, v113
	v_pk_add_f32 v[56:57], v[60:61], v[54:55]
	s_add_i32 s68, s69, s46
	v_lshl_or_b32 v10, v31, 16, v10
	v_and_or_b32 v11, v31, s0, v11
	v_lshlrev_b32_e32 v14, 16, v114
	v_and_b32_e32 v15, 0xffff0000, v114
	v_pk_add_f32 v[52:53], v[56:57], v[50:51]
	s_cmpk_gt_i32 s68, 0xfff
	ds_write2_b32 v122, v10, v11 offset0:216 offset1:252
	ds_write_b128 v123, v[32:35]
	ds_write_b128 v124, v[36:39]
	ds_write_b128 v125, v[40:43]
	ds_write_b128 v126, v[44:47]
	v_lshlrev_b32_e32 v10, 16, v115
	v_and_b32_e32 v11, 0xffff0000, v115
	v_pk_add_f32 v[48:49], v[52:53], v[14:15]
	s_cselect_b64 s[66:67], -1, 0
	v_pk_add_f32 v[12:13], v[48:49], v[10:11]
	s_and_b64 vcc, exec, s[66:67]
	ds_write_b64 v117, v[12:13]
	s_cbranch_vccnz .LBB0_119
	v_readlane_b32 s0, v252, 56
	s_add_i32 s0, s0, s47
	s_and_b32 s0, s0, 0xf00
	s_ashr_i32 s34, s68, 4
	s_add_i32 s36, s0, s34
	s_ashr_i32 s37, s36, 31
	s_lshr_b32 s0, s37, 24
	s_add_i32 s0, s36, s0
	s_and_b32 s34, s0, 0xffffff00
	s_sub_i32 s34, s36, s34
	s_ashr_i32 s38, s0, 11
	s_ashr_i32 s39, s38, 31
	s_ashr_i32 s35, s34, 31
	s_lshl_b64 s[38:39], s[38:39], 14
	s_lshl_b64 s[34:35], s[34:35], 6
	s_add_u32 s38, s38, s34
	s_addc_u32 s39, s39, s35
	s_add_u32 s34, s38, s49
	v_readlane_b32 s35, v254, 39
	s_addc_u32 s35, s39, s35
	s_lshr_b32 s0, s0, 1
	s_and_b32 s0, s0, 0x380
	v_or_b32_e32 v24, s0, v116
	s_lshl_b64 s[34:35], s[34:35], 11
	v_lshl_or_b32 v24, v24, 1, s34
	v_mov_b32_e32 v25, s35
	v_or_b32_e32 v30, 0x800, v24
	v_mov_b32_e32 v31, s35
	v_or_b32_e32 v34, 0x1000, v24
	v_mov_b32_e32 v35, s35
	v_lshl_add_u64 v[26:27], s[70:71], 0, v[24:25]
	v_lshl_add_u64 v[32:33], s[70:71], 0, v[30:31]
	v_lshl_add_u64 v[30:31], s[72:73], 0, v[30:31]
	v_lshl_add_u64 v[36:37], s[70:71], 0, v[34:35]
	v_lshl_add_u64 v[34:35], s[72:73], 0, v[34:35]
	v_or_b32_e32 v38, 0x1800, v24
	v_mov_b32_e32 v39, s35
	v_lshl_add_u64 v[28:29], s[72:73], 0, v[24:25]
	v_lshl_add_u64 v[40:41], s[70:71], 0, v[38:39]
	v_lshl_add_u64 v[38:39], s[72:73], 0, v[38:39]
	global_load_dword v79, v[26:27], off
	global_load_dword v133, v[28:29], off nt
	global_load_dword v89, v[32:33], off
	global_load_dword v134, v[30:31], off nt
	global_load_dword v110, v[36:37], off
	global_load_dword v135, v[34:35], off nt
	global_load_dword v111, v[40:41], off
	global_load_dword v136, v[38:39], off nt
	v_or_b32_e32 v26, 0x2000, v24
	v_mov_b32_e32 v27, s35
	v_or_b32_e32 v30, 0x2800, v24
	v_or_b32_e32 v34, 0x3000, v24
	v_or_b32_e32 v24, 0x3800, v24
	v_lshl_add_u64 v[28:29], s[70:71], 0, v[26:27]
	v_mov_b32_e32 v31, s35
	v_mov_b32_e32 v35, s35
	v_lshl_add_u64 v[38:39], s[70:71], 0, v[24:25]
	v_lshl_add_u64 v[24:25], s[72:73], 0, v[24:25]
	v_mov_b32_e32 v103, s39
	v_or_b32_e32 v102, s38, v78
	v_lshl_add_u64 v[26:27], s[72:73], 0, v[26:27]
	v_lshl_add_u64 v[32:33], s[70:71], 0, v[30:31]
	v_lshl_add_u64 v[30:31], s[72:73], 0, v[30:31]
	v_lshl_add_u64 v[36:37], s[70:71], 0, v[34:35]
	v_lshl_add_u64 v[34:35], s[72:73], 0, v[34:35]
	global_load_dword v112, v[28:29], off
	global_load_dword v137, v[26:27], off nt
	global_load_dword v113, v[32:33], off
	global_load_dword v138, v[30:31], off nt
	global_load_dword v114, v[36:37], off
	global_load_dword v139, v[34:35], off nt
	global_load_dword v115, v[38:39], off
	global_load_dword v140, v[24:25], off nt
	v_mov_b32_e32 v25, s39
	v_or_b32_e32 v24, s38, v88
	v_lshlrev_b64 v[102:103], 11, v[102:103]
	v_lshlrev_b64 v[24:25], 11, v[24:25]
	s_lshl_b32 s0, s0, 1
	v_lshl_add_u64 v[102:103], s[96:97], 0, v[102:103]
	v_lshl_add_u64 v[24:25], s[94:95], 0, v[24:25]
	s_lshl_b64 s[34:35], s[36:37], 15
	v_lshl_add_u64 v[102:103], v[102:103], 0, s[0:1]
	v_lshl_add_u64 v[24:25], v[24:25], 0, s[0:1]
	v_lshl_add_u64 v[40:41], v[90:91], 0, s[34:35]
	v_lshl_add_u64 v[102:103], s[90:91], 1, v[102:103]
	v_lshl_add_u64 v[28:29], v[76:77], 1, v[24:25]
	v_lshl_add_u64 v[32:33], v[40:41], 0, v[94:95]
	v_lshl_add_u64 v[36:37], v[40:41], 0, v[96:97]
	v_lshl_add_u64 v[42:43], v[40:41], 0, v[98:99]
	v_lshl_add_u64 v[44:45], v[40:41], 0, v[100:101]
	v_lshl_add_u64 v[108:109], v[102:103], 0, v[0:1]
	global_load_dwordx4 v[24:27], v[28:29], off
	s_nop 0
	global_load_dwordx4 v[28:31], v[28:29], off offset:2048
	s_nop 0
	global_load_dwordx4 v[32:35], v[32:33], off nt
	s_nop 0
	global_load_dwordx4 v[36:39], v[36:37], off nt
	s_nop 0
	global_load_dwordx4 v[40:43], v[42:43], off nt
	s_nop 0
	global_load_dwordx4 v[44:47], v[44:45], off nt
	s_nop 0
	global_load_dwordx2 v[102:103], v[108:109], off nt
	global_load_dwordx2 v[104:105], v[108:109], off offset:32 nt
	global_load_dwordx2 v[106:107], v[108:109], off offset:64 nt
	s_nop 0
	global_load_dwordx2 v[108:109], v[108:109], off offset:96 nt
